# m_comb chunk scan: hand-written 64-chunk batch loop (SGPR-base addressing, gate pairs fetched from LDS in bulk instead of one lgkmcnt(0) round trip per element)
# speedup vs baseline: 1.0060x; 1.0037x over previous
; DI unsigned pk2(float lo, float hi) { f32x2 v = {lo, hi}; bf16x2_t b = __builtin_convertvector(v, bf16x2_t); return __builtin_bit_cast(unsigned, b); }
; DI float bflo(unsigned u) { return __uint_as_float(u << 16); }
; DI float bfhi(unsigned u) { return __uint_as_float(u & 0xffff0000u); }
; DI void phase_m_comb(int wv, const ArgP a, LAS unsigned char* lds, int dry) {
;     ...
;         if (eb < 128) { const int h = eb >> 5; unsigned* p = (unsigned*)(CST + (size_t)h * 32768 + (size_t)(eb & 31) * 1024 + 2 * tid); float C0 = 0.f, C1 = 0.f;
;             for (int c = 0; c < 256; c += 64) { unsigned d[64];
; #pragma unroll
;                 for (int k = 0; k < 64; ++k) d[k] = p[(size_t)(c + k) * 65536];
; #pragma unroll
;                 for (int k = 0; k < 64; ++k) { if (!dry) p[(size_t)(c + k) * 65536] = pk2(C0, C1); const float a_ = ga[(c + k) * 4 + h], b_ = gb[(c + k) * 4 + h]; C0 = a_ * C0 + b_ * bflo(d[k]); C1 = a_ * C1 + b_ * bfhi(d[k]); } }
.LBB0_1543:
	s_cmpk_lg_i32 s13, 0x80
	s_mov_b64 s[0:1], -1
	s_cbranch_scc0 .LBB0_1547
	s_ashr_i32 s8, s13, 5
	s_ashr_i32 s9, s8, 31
	s_lshl_b64 s[0:1], s[8:9], 16
	s_add_u32 s0, s10, s0
	s_addc_u32 s1, s11, s1
	s_lshl_b32 s2, s13, 11
	s_and_b32 s2, s2, 0xf800
	s_add_u32 s0, s0, s2
	s_addc_u32 s1, s1, 0
	v_lshlrev_b32_e32 v116, 1, v0
	s_mov_b64 s[14:15], s[0:1]
	s_mov_b64 s[16:17], s[0:1]
	s_lshl_b32 s2, s8, 2
	s_add_i32 s18, s2, 0x2000
	s_add_i32 s19, s2, 0x3000
	v_mov_b32_e32 v8, 0
	v_mov_b32_e32 v9, 0
	s_mov_b32 s0, 0
.Lmc_batch:
	v_mov_b32_e32 v118, s18
	v_mov_b32_e32 v119, s19
	global_load_dword v140, v116, s[14:15]
	s_add_u32 s14, s14, 0x40000
	s_addc_u32 s15, s15, 0
	global_load_dword v141, v116, s[14:15]
	s_add_u32 s14, s14, 0x40000
	s_addc_u32 s15, s15, 0
	global_load_dword v142, v116, s[14:15]
	s_add_u32 s14, s14, 0x40000
	s_addc_u32 s15, s15, 0
	global_load_dword v143, v116, s[14:15]
	s_add_u32 s14, s14, 0x40000
	s_addc_u32 s15, s15, 0
	global_load_dword v144, v116, s[14:15]
	s_add_u32 s14, s14, 0x40000
	s_addc_u32 s15, s15, 0
	global_load_dword v145, v116, s[14:15]
	s_add_u32 s14, s14, 0x40000
	s_addc_u32 s15, s15, 0
	global_load_dword v146, v116, s[14:15]
	s_add_u32 s14, s14, 0x40000
	s_addc_u32 s15, s15, 0
	global_load_dword v147, v116, s[14:15]
	s_add_u32 s14, s14, 0x40000
	s_addc_u32 s15, s15, 0
	ds_read2_b32 v[12:13], v118 offset0:0 offset1:4
	ds_read2_b32 v[76:77], v119 offset0:0 offset1:4
	ds_read2_b32 v[14:15], v118 offset0:8 offset1:12
	ds_read2_b32 v[78:79], v119 offset0:8 offset1:12
	ds_read2_b32 v[16:17], v118 offset0:16 offset1:20
	ds_read2_b32 v[80:81], v119 offset0:16 offset1:20
	ds_read2_b32 v[18:19], v118 offset0:24 offset1:28
	ds_read2_b32 v[82:83], v119 offset0:24 offset1:28
	global_load_dword v148, v116, s[14:15]
	s_add_u32 s14, s14, 0x40000
	s_addc_u32 s15, s15, 0
	global_load_dword v149, v116, s[14:15]
	s_add_u32 s14, s14, 0x40000
	s_addc_u32 s15, s15, 0
	global_load_dword v150, v116, s[14:15]
	s_add_u32 s14, s14, 0x40000
	s_addc_u32 s15, s15, 0
	global_load_dword v151, v116, s[14:15]
	s_add_u32 s14, s14, 0x40000
	s_addc_u32 s15, s15, 0
	global_load_dword v152, v116, s[14:15]
	s_add_u32 s14, s14, 0x40000
	s_addc_u32 s15, s15, 0
	global_load_dword v153, v116, s[14:15]
	s_add_u32 s14, s14, 0x40000
	s_addc_u32 s15, s15, 0
	global_load_dword v154, v116, s[14:15]
	s_add_u32 s14, s14, 0x40000
	s_addc_u32 s15, s15, 0
	global_load_dword v155, v116, s[14:15]
	s_add_u32 s14, s14, 0x40000
	s_addc_u32 s15, s15, 0
	s_waitcnt lgkmcnt(0)
	ds_read2_b32 v[20:21], v118 offset0:32 offset1:36
	ds_read2_b32 v[84:85], v119 offset0:32 offset1:36
	ds_read2_b32 v[22:23], v118 offset0:40 offset1:44
	ds_read2_b32 v[86:87], v119 offset0:40 offset1:44
	ds_read2_b32 v[24:25], v118 offset0:48 offset1:52
	ds_read2_b32 v[88:89], v119 offset0:48 offset1:52
	ds_read2_b32 v[26:27], v118 offset0:56 offset1:60
	ds_read2_b32 v[90:91], v119 offset0:56 offset1:60
	global_load_dword v156, v116, s[14:15]
	s_add_u32 s14, s14, 0x40000
	s_addc_u32 s15, s15, 0
	global_load_dword v157, v116, s[14:15]
	s_add_u32 s14, s14, 0x40000
	s_addc_u32 s15, s15, 0
	global_load_dword v158, v116, s[14:15]
	s_add_u32 s14, s14, 0x40000
	s_addc_u32 s15, s15, 0
	global_load_dword v159, v116, s[14:15]
	s_add_u32 s14, s14, 0x40000
	s_addc_u32 s15, s15, 0
	global_load_dword v160, v116, s[14:15]
	s_add_u32 s14, s14, 0x40000
	s_addc_u32 s15, s15, 0
	global_load_dword v161, v116, s[14:15]
	s_add_u32 s14, s14, 0x40000
	s_addc_u32 s15, s15, 0
	global_load_dword v162, v116, s[14:15]
	s_add_u32 s14, s14, 0x40000
	s_addc_u32 s15, s15, 0
	global_load_dword v163, v116, s[14:15]
	s_add_u32 s14, s14, 0x40000
	s_addc_u32 s15, s15, 0
	s_waitcnt lgkmcnt(0)
	ds_read2_b32 v[28:29], v118 offset0:64 offset1:68
	ds_read2_b32 v[92:93], v119 offset0:64 offset1:68
	ds_read2_b32 v[30:31], v118 offset0:72 offset1:76
	ds_read2_b32 v[94:95], v119 offset0:72 offset1:76
	ds_read2_b32 v[32:33], v118 offset0:80 offset1:84
	ds_read2_b32 v[96:97], v119 offset0:80 offset1:84
	ds_read2_b32 v[34:35], v118 offset0:88 offset1:92
	ds_read2_b32 v[98:99], v119 offset0:88 offset1:92
	global_load_dword v164, v116, s[14:15]
	s_add_u32 s14, s14, 0x40000
	s_addc_u32 s15, s15, 0
	global_load_dword v165, v116, s[14:15]
	s_add_u32 s14, s14, 0x40000
	s_addc_u32 s15, s15, 0
	global_load_dword v166, v116, s[14:15]
	s_add_u32 s14, s14, 0x40000
	s_addc_u32 s15, s15, 0
	global_load_dword v167, v116, s[14:15]
	s_add_u32 s14, s14, 0x40000
	s_addc_u32 s15, s15, 0
	global_load_dword v168, v116, s[14:15]
	s_add_u32 s14, s14, 0x40000
	s_addc_u32 s15, s15, 0
	global_load_dword v169, v116, s[14:15]
	s_add_u32 s14, s14, 0x40000
	s_addc_u32 s15, s15, 0
	global_load_dword v170, v116, s[14:15]
	s_add_u32 s14, s14, 0x40000
	s_addc_u32 s15, s15, 0
	global_load_dword v171, v116, s[14:15]
	s_add_u32 s14, s14, 0x40000
	s_addc_u32 s15, s15, 0
	s_waitcnt lgkmcnt(0)
	ds_read2_b32 v[36:37], v118 offset0:96 offset1:100
	ds_read2_b32 v[100:101], v119 offset0:96 offset1:100
	ds_read2_b32 v[38:39], v118 offset0:104 offset1:108
	ds_read2_b32 v[102:103], v119 offset0:104 offset1:108
	ds_read2_b32 v[40:41], v118 offset0:112 offset1:116
	ds_read2_b32 v[104:105], v119 offset0:112 offset1:116
	ds_read2_b32 v[42:43], v118 offset0:120 offset1:124
	ds_read2_b32 v[106:107], v119 offset0:120 offset1:124
	global_load_dword v172, v116, s[14:15]
	s_add_u32 s14, s14, 0x40000
	s_addc_u32 s15, s15, 0
	global_load_dword v173, v116, s[14:15]
	s_add_u32 s14, s14, 0x40000
	s_addc_u32 s15, s15, 0
	global_load_dword v174, v116, s[14:15]
	s_add_u32 s14, s14, 0x40000
	s_addc_u32 s15, s15, 0
	global_load_dword v175, v116, s[14:15]
	s_add_u32 s14, s14, 0x40000
	s_addc_u32 s15, s15, 0
	global_load_dword v176, v116, s[14:15]
	s_add_u32 s14, s14, 0x40000
	s_addc_u32 s15, s15, 0
	global_load_dword v177, v116, s[14:15]
	s_add_u32 s14, s14, 0x40000
	s_addc_u32 s15, s15, 0
	global_load_dword v178, v116, s[14:15]
	s_add_u32 s14, s14, 0x40000
	s_addc_u32 s15, s15, 0
	global_load_dword v179, v116, s[14:15]
	s_add_u32 s14, s14, 0x40000
	s_addc_u32 s15, s15, 0
	s_waitcnt lgkmcnt(0)
; DI unsigned pk2(float lo, float hi) { f32x2 v = {lo, hi}; bf16x2_t b = __builtin_convertvector(v, bf16x2_t); return __builtin_bit_cast(unsigned, b); }
; DI float bflo(unsigned u) { return __uint_as_float(u << 16); }
; DI float bfhi(unsigned u) { return __uint_as_float(u & 0xffff0000u); }
; DI void phase_m_comb(int wv, const ArgP a, LAS unsigned char* lds, int dry) {
;     ...
;             for (int c = 0; c < 256; c += 64) { unsigned d[64];
; #pragma unroll
;                 for (int k = 0; k < 64; ++k) d[k] = p[(size_t)(c + k) * 65536];
; #pragma unroll
;                 for (int k = 0; k < 64; ++k) { if (!dry) p[(size_t)(c + k) * 65536] = pk2(C0, C1); const float a_ = ga[(c + k) * 4 + h], b_ = gb[(c + k) * 4 + h]; C0 = a_ * C0 + b_ * bflo(d[k]); C1 = a_ * C1 + b_ * bfhi(d[k]); } }
	ds_read2_b32 v[44:45], v118 offset0:128 offset1:132
	ds_read2_b32 v[108:109], v119 offset0:128 offset1:132
	ds_read2_b32 v[46:47], v118 offset0:136 offset1:140
	ds_read2_b32 v[110:111], v119 offset0:136 offset1:140
	ds_read2_b32 v[48:49], v118 offset0:144 offset1:148
	ds_read2_b32 v[112:113], v119 offset0:144 offset1:148
	ds_read2_b32 v[50:51], v118 offset0:152 offset1:156
	ds_read2_b32 v[114:115], v119 offset0:152 offset1:156
	global_load_dword v180, v116, s[14:15]
	s_add_u32 s14, s14, 0x40000
	s_addc_u32 s15, s15, 0
	global_load_dword v181, v116, s[14:15]
	s_add_u32 s14, s14, 0x40000
	s_addc_u32 s15, s15, 0
	global_load_dword v182, v116, s[14:15]
	s_add_u32 s14, s14, 0x40000
	s_addc_u32 s15, s15, 0
	global_load_dword v183, v116, s[14:15]
	s_add_u32 s14, s14, 0x40000
	s_addc_u32 s15, s15, 0
	global_load_dword v184, v116, s[14:15]
	s_add_u32 s14, s14, 0x40000
	s_addc_u32 s15, s15, 0
	global_load_dword v185, v116, s[14:15]
	s_add_u32 s14, s14, 0x40000
	s_addc_u32 s15, s15, 0
	global_load_dword v186, v116, s[14:15]
	s_add_u32 s14, s14, 0x40000
	s_addc_u32 s15, s15, 0
	global_load_dword v187, v116, s[14:15]
	s_add_u32 s14, s14, 0x40000
	s_addc_u32 s15, s15, 0
	s_waitcnt lgkmcnt(0)
	ds_read2_b32 v[52:53], v118 offset0:160 offset1:164
	ds_read2_b32 v[208:209], v119 offset0:160 offset1:164
	ds_read2_b32 v[54:55], v118 offset0:168 offset1:172
	ds_read2_b32 v[210:211], v119 offset0:168 offset1:172
	ds_read2_b32 v[56:57], v118 offset0:176 offset1:180
	ds_read2_b32 v[212:213], v119 offset0:176 offset1:180
	ds_read2_b32 v[58:59], v118 offset0:184 offset1:188
	ds_read2_b32 v[214:215], v119 offset0:184 offset1:188
	global_load_dword v188, v116, s[14:15]
	s_add_u32 s14, s14, 0x40000
	s_addc_u32 s15, s15, 0
	global_load_dword v189, v116, s[14:15]
	s_add_u32 s14, s14, 0x40000
	s_addc_u32 s15, s15, 0
	global_load_dword v190, v116, s[14:15]
	s_add_u32 s14, s14, 0x40000
	s_addc_u32 s15, s15, 0
	global_load_dword v191, v116, s[14:15]
	s_add_u32 s14, s14, 0x40000
	s_addc_u32 s15, s15, 0
	global_load_dword v196, v116, s[14:15]
	s_add_u32 s14, s14, 0x40000
	s_addc_u32 s15, s15, 0
	global_load_dword v197, v116, s[14:15]
	s_add_u32 s14, s14, 0x40000
	s_addc_u32 s15, s15, 0
	global_load_dword v198, v116, s[14:15]
	s_add_u32 s14, s14, 0x40000
	s_addc_u32 s15, s15, 0
	global_load_dword v199, v116, s[14:15]
	s_add_u32 s14, s14, 0x40000
	s_addc_u32 s15, s15, 0
	s_waitcnt lgkmcnt(0)
	ds_read2_b32 v[60:61], v118 offset0:192 offset1:196
	ds_read2_b32 v[216:217], v119 offset0:192 offset1:196
	ds_read2_b32 v[62:63], v118 offset0:200 offset1:204
	ds_read2_b32 v[218:219], v119 offset0:200 offset1:204
	ds_read2_b32 v[64:65], v118 offset0:208 offset1:212
	ds_read2_b32 v[220:221], v119 offset0:208 offset1:212
	ds_read2_b32 v[66:67], v118 offset0:216 offset1:220
	ds_read2_b32 v[222:223], v119 offset0:216 offset1:220
	global_load_dword v200, v116, s[14:15]
	s_add_u32 s14, s14, 0x40000
	s_addc_u32 s15, s15, 0
	global_load_dword v201, v116, s[14:15]
	s_add_u32 s14, s14, 0x40000
	s_addc_u32 s15, s15, 0
	global_load_dword v202, v116, s[14:15]
	s_add_u32 s14, s14, 0x40000
	s_addc_u32 s15, s15, 0
	global_load_dword v203, v116, s[14:15]
	s_add_u32 s14, s14, 0x40000
	s_addc_u32 s15, s15, 0
	global_load_dword v204, v116, s[14:15]
	s_add_u32 s14, s14, 0x40000
	s_addc_u32 s15, s15, 0
	global_load_dword v205, v116, s[14:15]
	s_add_u32 s14, s14, 0x40000
	s_addc_u32 s15, s15, 0
	global_load_dword v206, v116, s[14:15]
	s_add_u32 s14, s14, 0x40000
	s_addc_u32 s15, s15, 0
	global_load_dword v207, v116, s[14:15]
	s_add_u32 s14, s14, 0x40000
	s_addc_u32 s15, s15, 0
	s_waitcnt lgkmcnt(0)
	ds_read2_b32 v[68:69], v118 offset0:224 offset1:228
	ds_read2_b32 v[224:225], v119 offset0:224 offset1:228
	ds_read2_b32 v[70:71], v118 offset0:232 offset1:236
	ds_read2_b32 v[226:227], v119 offset0:232 offset1:236
	ds_read2_b32 v[72:73], v118 offset0:240 offset1:244
	ds_read2_b32 v[228:229], v119 offset0:240 offset1:244
	ds_read2_b32 v[74:75], v118 offset0:248 offset1:252
	ds_read2_b32 v[230:231], v119 offset0:248 offset1:252
	s_waitcnt lgkmcnt(0)
	s_waitcnt vmcnt(63)
	v_cvt_pk_bf16_f32 v122, v8, v9
	v_lshlrev_b32_e32 v120, 16, v140
	v_and_b32_e32 v121, 0xffff0000, v140
	global_store_dword v116, v122, s[16:17]
	s_add_u32 s16, s16, 0x40000
	s_addc_u32 s17, s17, 0
	v_pk_mul_f32 v[120:121], v[76:77], v[120:121] op_sel_hi:[0,1]
	v_pk_fma_f32 v[8:9], v[8:9], v[12:13], v[120:121] op_sel_hi:[1,0,1]
	s_waitcnt vmcnt(63)
	v_cvt_pk_bf16_f32 v123, v8, v9
	v_lshlrev_b32_e32 v120, 16, v141
	v_and_b32_e32 v121, 0xffff0000, v141
	global_store_dword v116, v123, s[16:17]
	s_add_u32 s16, s16, 0x40000
	s_addc_u32 s17, s17, 0
	v_pk_mul_f32 v[120:121], v[76:77], v[120:121] op_sel:[1,0] op_sel_hi:[1,1]
	v_pk_fma_f32 v[8:9], v[8:9], v[12:13], v[120:121] op_sel:[0,1,0] op_sel_hi:[1,1,1]
	s_waitcnt vmcnt(63)
	v_cvt_pk_bf16_f32 v122, v8, v9
	v_lshlrev_b32_e32 v120, 16, v142
	v_and_b32_e32 v121, 0xffff0000, v142
	global_store_dword v116, v122, s[16:17]
	s_add_u32 s16, s16, 0x40000
	s_addc_u32 s17, s17, 0
	v_pk_mul_f32 v[120:121], v[78:79], v[120:121] op_sel_hi:[0,1]
	v_pk_fma_f32 v[8:9], v[8:9], v[14:15], v[120:121] op_sel_hi:[1,0,1]
	s_waitcnt vmcnt(63)
	v_cvt_pk_bf16_f32 v123, v8, v9
	v_lshlrev_b32_e32 v120, 16, v143
	v_and_b32_e32 v121, 0xffff0000, v143
	global_store_dword v116, v123, s[16:17]
	s_add_u32 s16, s16, 0x40000
	s_addc_u32 s17, s17, 0
	v_pk_mul_f32 v[120:121], v[78:79], v[120:121] op_sel:[1,0] op_sel_hi:[1,1]
	v_pk_fma_f32 v[8:9], v[8:9], v[14:15], v[120:121] op_sel:[0,1,0] op_sel_hi:[1,1,1]
	s_waitcnt vmcnt(63)
; DI unsigned pk2(float lo, float hi) { f32x2 v = {lo, hi}; bf16x2_t b = __builtin_convertvector(v, bf16x2_t); return __builtin_bit_cast(unsigned, b); }
; DI float bflo(unsigned u) { return __uint_as_float(u << 16); }
; DI float bfhi(unsigned u) { return __uint_as_float(u & 0xffff0000u); }
; DI void phase_m_comb(int wv, const ArgP a, LAS unsigned char* lds, int dry) {
;     ...
;             for (int c = 0; c < 256; c += 64) { unsigned d[64];
; #pragma unroll
;                 for (int k = 0; k < 64; ++k) d[k] = p[(size_t)(c + k) * 65536];
; #pragma unroll
;                 for (int k = 0; k < 64; ++k) { if (!dry) p[(size_t)(c + k) * 65536] = pk2(C0, C1); const float a_ = ga[(c + k) * 4 + h], b_ = gb[(c + k) * 4 + h]; C0 = a_ * C0 + b_ * bflo(d[k]); C1 = a_ * C1 + b_ * bfhi(d[k]); } }
	v_cvt_pk_bf16_f32 v122, v8, v9
	v_lshlrev_b32_e32 v120, 16, v144
	v_and_b32_e32 v121, 0xffff0000, v144
	global_store_dword v116, v122, s[16:17]
	s_add_u32 s16, s16, 0x40000
	s_addc_u32 s17, s17, 0
	v_pk_mul_f32 v[120:121], v[80:81], v[120:121] op_sel_hi:[0,1]
	v_pk_fma_f32 v[8:9], v[8:9], v[16:17], v[120:121] op_sel_hi:[1,0,1]
	s_waitcnt vmcnt(63)
	v_cvt_pk_bf16_f32 v123, v8, v9
	v_lshlrev_b32_e32 v120, 16, v145
	v_and_b32_e32 v121, 0xffff0000, v145
	global_store_dword v116, v123, s[16:17]
	s_add_u32 s16, s16, 0x40000
	s_addc_u32 s17, s17, 0
	v_pk_mul_f32 v[120:121], v[80:81], v[120:121] op_sel:[1,0] op_sel_hi:[1,1]
	v_pk_fma_f32 v[8:9], v[8:9], v[16:17], v[120:121] op_sel:[0,1,0] op_sel_hi:[1,1,1]
	s_waitcnt vmcnt(63)
	v_cvt_pk_bf16_f32 v122, v8, v9
	v_lshlrev_b32_e32 v120, 16, v146
	v_and_b32_e32 v121, 0xffff0000, v146
	global_store_dword v116, v122, s[16:17]
	s_add_u32 s16, s16, 0x40000
	s_addc_u32 s17, s17, 0
	v_pk_mul_f32 v[120:121], v[82:83], v[120:121] op_sel_hi:[0,1]
	v_pk_fma_f32 v[8:9], v[8:9], v[18:19], v[120:121] op_sel_hi:[1,0,1]
	s_waitcnt vmcnt(63)
	v_cvt_pk_bf16_f32 v123, v8, v9
	v_lshlrev_b32_e32 v120, 16, v147
	v_and_b32_e32 v121, 0xffff0000, v147
	global_store_dword v116, v123, s[16:17]
	s_add_u32 s16, s16, 0x40000
	s_addc_u32 s17, s17, 0
	v_pk_mul_f32 v[120:121], v[82:83], v[120:121] op_sel:[1,0] op_sel_hi:[1,1]
	v_pk_fma_f32 v[8:9], v[8:9], v[18:19], v[120:121] op_sel:[0,1,0] op_sel_hi:[1,1,1]
	s_waitcnt vmcnt(63)
	v_cvt_pk_bf16_f32 v122, v8, v9
	v_lshlrev_b32_e32 v120, 16, v148
	v_and_b32_e32 v121, 0xffff0000, v148
	global_store_dword v116, v122, s[16:17]
	s_add_u32 s16, s16, 0x40000
	s_addc_u32 s17, s17, 0
	v_pk_mul_f32 v[120:121], v[84:85], v[120:121] op_sel_hi:[0,1]
	v_pk_fma_f32 v[8:9], v[8:9], v[20:21], v[120:121] op_sel_hi:[1,0,1]
	s_waitcnt vmcnt(63)
	v_cvt_pk_bf16_f32 v123, v8, v9
	v_lshlrev_b32_e32 v120, 16, v149
	v_and_b32_e32 v121, 0xffff0000, v149
	global_store_dword v116, v123, s[16:17]
	s_add_u32 s16, s16, 0x40000
	s_addc_u32 s17, s17, 0
	v_pk_mul_f32 v[120:121], v[84:85], v[120:121] op_sel:[1,0] op_sel_hi:[1,1]
	v_pk_fma_f32 v[8:9], v[8:9], v[20:21], v[120:121] op_sel:[0,1,0] op_sel_hi:[1,1,1]
	s_waitcnt vmcnt(63)
	v_cvt_pk_bf16_f32 v122, v8, v9
	v_lshlrev_b32_e32 v120, 16, v150
	v_and_b32_e32 v121, 0xffff0000, v150
	global_store_dword v116, v122, s[16:17]
	s_add_u32 s16, s16, 0x40000
	s_addc_u32 s17, s17, 0
	v_pk_mul_f32 v[120:121], v[86:87], v[120:121] op_sel_hi:[0,1]
	v_pk_fma_f32 v[8:9], v[8:9], v[22:23], v[120:121] op_sel_hi:[1,0,1]
	s_waitcnt vmcnt(63)
	v_cvt_pk_bf16_f32 v123, v8, v9
	v_lshlrev_b32_e32 v120, 16, v151
	v_and_b32_e32 v121, 0xffff0000, v151
	global_store_dword v116, v123, s[16:17]
	s_add_u32 s16, s16, 0x40000
	s_addc_u32 s17, s17, 0
	v_pk_mul_f32 v[120:121], v[86:87], v[120:121] op_sel:[1,0] op_sel_hi:[1,1]
	v_pk_fma_f32 v[8:9], v[8:9], v[22:23], v[120:121] op_sel:[0,1,0] op_sel_hi:[1,1,1]
	s_waitcnt vmcnt(63)
	v_cvt_pk_bf16_f32 v122, v8, v9
	v_lshlrev_b32_e32 v120, 16, v152
	v_and_b32_e32 v121, 0xffff0000, v152
	global_store_dword v116, v122, s[16:17]
	s_add_u32 s16, s16, 0x40000
	s_addc_u32 s17, s17, 0
	v_pk_mul_f32 v[120:121], v[88:89], v[120:121] op_sel_hi:[0,1]
	v_pk_fma_f32 v[8:9], v[8:9], v[24:25], v[120:121] op_sel_hi:[1,0,1]
	s_waitcnt vmcnt(63)
	v_cvt_pk_bf16_f32 v123, v8, v9
	v_lshlrev_b32_e32 v120, 16, v153
	v_and_b32_e32 v121, 0xffff0000, v153
	global_store_dword v116, v123, s[16:17]
	s_add_u32 s16, s16, 0x40000
	s_addc_u32 s17, s17, 0
	v_pk_mul_f32 v[120:121], v[88:89], v[120:121] op_sel:[1,0] op_sel_hi:[1,1]
	v_pk_fma_f32 v[8:9], v[8:9], v[24:25], v[120:121] op_sel:[0,1,0] op_sel_hi:[1,1,1]
	s_waitcnt vmcnt(63)
	v_cvt_pk_bf16_f32 v122, v8, v9
	v_lshlrev_b32_e32 v120, 16, v154
	v_and_b32_e32 v121, 0xffff0000, v154
	global_store_dword v116, v122, s[16:17]
	s_add_u32 s16, s16, 0x40000
	s_addc_u32 s17, s17, 0
	v_pk_mul_f32 v[120:121], v[90:91], v[120:121] op_sel_hi:[0,1]
	v_pk_fma_f32 v[8:9], v[8:9], v[26:27], v[120:121] op_sel_hi:[1,0,1]
	s_waitcnt vmcnt(63)
	v_cvt_pk_bf16_f32 v123, v8, v9
	v_lshlrev_b32_e32 v120, 16, v155
	v_and_b32_e32 v121, 0xffff0000, v155
	global_store_dword v116, v123, s[16:17]
	s_add_u32 s16, s16, 0x40000
	s_addc_u32 s17, s17, 0
	v_pk_mul_f32 v[120:121], v[90:91], v[120:121] op_sel:[1,0] op_sel_hi:[1,1]
	v_pk_fma_f32 v[8:9], v[8:9], v[26:27], v[120:121] op_sel:[0,1,0] op_sel_hi:[1,1,1]
	s_waitcnt vmcnt(63)
	v_cvt_pk_bf16_f32 v122, v8, v9
	v_lshlrev_b32_e32 v120, 16, v156
	v_and_b32_e32 v121, 0xffff0000, v156
	global_store_dword v116, v122, s[16:17]
	s_add_u32 s16, s16, 0x40000
	s_addc_u32 s17, s17, 0
	v_pk_mul_f32 v[120:121], v[92:93], v[120:121] op_sel_hi:[0,1]
	v_pk_fma_f32 v[8:9], v[8:9], v[28:29], v[120:121] op_sel_hi:[1,0,1]
	s_waitcnt vmcnt(63)
	v_cvt_pk_bf16_f32 v123, v8, v9
	v_lshlrev_b32_e32 v120, 16, v157
	v_and_b32_e32 v121, 0xffff0000, v157
	global_store_dword v116, v123, s[16:17]
	s_add_u32 s16, s16, 0x40000
	s_addc_u32 s17, s17, 0
	v_pk_mul_f32 v[120:121], v[92:93], v[120:121] op_sel:[1,0] op_sel_hi:[1,1]
	v_pk_fma_f32 v[8:9], v[8:9], v[28:29], v[120:121] op_sel:[0,1,0] op_sel_hi:[1,1,1]
	s_waitcnt vmcnt(63)
	v_cvt_pk_bf16_f32 v122, v8, v9
	v_lshlrev_b32_e32 v120, 16, v158
	v_and_b32_e32 v121, 0xffff0000, v158
	global_store_dword v116, v122, s[16:17]
	s_add_u32 s16, s16, 0x40000
	s_addc_u32 s17, s17, 0
	v_pk_mul_f32 v[120:121], v[94:95], v[120:121] op_sel_hi:[0,1]
	v_pk_fma_f32 v[8:9], v[8:9], v[30:31], v[120:121] op_sel_hi:[1,0,1]
	s_waitcnt vmcnt(63)
; DI unsigned pk2(float lo, float hi) { f32x2 v = {lo, hi}; bf16x2_t b = __builtin_convertvector(v, bf16x2_t); return __builtin_bit_cast(unsigned, b); }
; DI float bflo(unsigned u) { return __uint_as_float(u << 16); }
; DI float bfhi(unsigned u) { return __uint_as_float(u & 0xffff0000u); }
; DI void phase_m_comb(int wv, const ArgP a, LAS unsigned char* lds, int dry) {
;     ...
;             for (int c = 0; c < 256; c += 64) { unsigned d[64];
; #pragma unroll
;                 for (int k = 0; k < 64; ++k) d[k] = p[(size_t)(c + k) * 65536];
; #pragma unroll
;                 for (int k = 0; k < 64; ++k) { if (!dry) p[(size_t)(c + k) * 65536] = pk2(C0, C1); const float a_ = ga[(c + k) * 4 + h], b_ = gb[(c + k) * 4 + h]; C0 = a_ * C0 + b_ * bflo(d[k]); C1 = a_ * C1 + b_ * bfhi(d[k]); } }
	v_cvt_pk_bf16_f32 v123, v8, v9
	v_lshlrev_b32_e32 v120, 16, v159
	v_and_b32_e32 v121, 0xffff0000, v159
	global_store_dword v116, v123, s[16:17]
	s_add_u32 s16, s16, 0x40000
	s_addc_u32 s17, s17, 0
	v_pk_mul_f32 v[120:121], v[94:95], v[120:121] op_sel:[1,0] op_sel_hi:[1,1]
	v_pk_fma_f32 v[8:9], v[8:9], v[30:31], v[120:121] op_sel:[0,1,0] op_sel_hi:[1,1,1]
	s_waitcnt vmcnt(63)
	v_cvt_pk_bf16_f32 v122, v8, v9
	v_lshlrev_b32_e32 v120, 16, v160
	v_and_b32_e32 v121, 0xffff0000, v160
	global_store_dword v116, v122, s[16:17]
	s_add_u32 s16, s16, 0x40000
	s_addc_u32 s17, s17, 0
	v_pk_mul_f32 v[120:121], v[96:97], v[120:121] op_sel_hi:[0,1]
	v_pk_fma_f32 v[8:9], v[8:9], v[32:33], v[120:121] op_sel_hi:[1,0,1]
	s_waitcnt vmcnt(63)
	v_cvt_pk_bf16_f32 v123, v8, v9
	v_lshlrev_b32_e32 v120, 16, v161
	v_and_b32_e32 v121, 0xffff0000, v161
	global_store_dword v116, v123, s[16:17]
	s_add_u32 s16, s16, 0x40000
	s_addc_u32 s17, s17, 0
	v_pk_mul_f32 v[120:121], v[96:97], v[120:121] op_sel:[1,0] op_sel_hi:[1,1]
	v_pk_fma_f32 v[8:9], v[8:9], v[32:33], v[120:121] op_sel:[0,1,0] op_sel_hi:[1,1,1]
	s_waitcnt vmcnt(63)
	v_cvt_pk_bf16_f32 v122, v8, v9
	v_lshlrev_b32_e32 v120, 16, v162
	v_and_b32_e32 v121, 0xffff0000, v162
	global_store_dword v116, v122, s[16:17]
	s_add_u32 s16, s16, 0x40000
	s_addc_u32 s17, s17, 0
	v_pk_mul_f32 v[120:121], v[98:99], v[120:121] op_sel_hi:[0,1]
	v_pk_fma_f32 v[8:9], v[8:9], v[34:35], v[120:121] op_sel_hi:[1,0,1]
	s_waitcnt vmcnt(63)
	v_cvt_pk_bf16_f32 v123, v8, v9
	v_lshlrev_b32_e32 v120, 16, v163
	v_and_b32_e32 v121, 0xffff0000, v163
	global_store_dword v116, v123, s[16:17]
	s_add_u32 s16, s16, 0x40000
	s_addc_u32 s17, s17, 0
	v_pk_mul_f32 v[120:121], v[98:99], v[120:121] op_sel:[1,0] op_sel_hi:[1,1]
	v_pk_fma_f32 v[8:9], v[8:9], v[34:35], v[120:121] op_sel:[0,1,0] op_sel_hi:[1,1,1]
	s_waitcnt vmcnt(63)
	v_cvt_pk_bf16_f32 v122, v8, v9
	v_lshlrev_b32_e32 v120, 16, v164
	v_and_b32_e32 v121, 0xffff0000, v164
	global_store_dword v116, v122, s[16:17]
	s_add_u32 s16, s16, 0x40000
	s_addc_u32 s17, s17, 0
	v_pk_mul_f32 v[120:121], v[100:101], v[120:121] op_sel_hi:[0,1]
	v_pk_fma_f32 v[8:9], v[8:9], v[36:37], v[120:121] op_sel_hi:[1,0,1]
	s_waitcnt vmcnt(63)
	v_cvt_pk_bf16_f32 v123, v8, v9
	v_lshlrev_b32_e32 v120, 16, v165
	v_and_b32_e32 v121, 0xffff0000, v165
	global_store_dword v116, v123, s[16:17]
	s_add_u32 s16, s16, 0x40000
	s_addc_u32 s17, s17, 0
	v_pk_mul_f32 v[120:121], v[100:101], v[120:121] op_sel:[1,0] op_sel_hi:[1,1]
	v_pk_fma_f32 v[8:9], v[8:9], v[36:37], v[120:121] op_sel:[0,1,0] op_sel_hi:[1,1,1]
	s_waitcnt vmcnt(63)
	v_cvt_pk_bf16_f32 v122, v8, v9
	v_lshlrev_b32_e32 v120, 16, v166
	v_and_b32_e32 v121, 0xffff0000, v166
	global_store_dword v116, v122, s[16:17]
	s_add_u32 s16, s16, 0x40000
	s_addc_u32 s17, s17, 0
	v_pk_mul_f32 v[120:121], v[102:103], v[120:121] op_sel_hi:[0,1]
	v_pk_fma_f32 v[8:9], v[8:9], v[38:39], v[120:121] op_sel_hi:[1,0,1]
	s_waitcnt vmcnt(63)
	v_cvt_pk_bf16_f32 v123, v8, v9
	v_lshlrev_b32_e32 v120, 16, v167
	v_and_b32_e32 v121, 0xffff0000, v167
	global_store_dword v116, v123, s[16:17]
	s_add_u32 s16, s16, 0x40000
	s_addc_u32 s17, s17, 0
	v_pk_mul_f32 v[120:121], v[102:103], v[120:121] op_sel:[1,0] op_sel_hi:[1,1]
	v_pk_fma_f32 v[8:9], v[8:9], v[38:39], v[120:121] op_sel:[0,1,0] op_sel_hi:[1,1,1]
	s_waitcnt vmcnt(63)
	v_cvt_pk_bf16_f32 v122, v8, v9
	v_lshlrev_b32_e32 v120, 16, v168
	v_and_b32_e32 v121, 0xffff0000, v168
	global_store_dword v116, v122, s[16:17]
	s_add_u32 s16, s16, 0x40000
	s_addc_u32 s17, s17, 0
	v_pk_mul_f32 v[120:121], v[104:105], v[120:121] op_sel_hi:[0,1]
	v_pk_fma_f32 v[8:9], v[8:9], v[40:41], v[120:121] op_sel_hi:[1,0,1]
	s_waitcnt vmcnt(63)
	v_cvt_pk_bf16_f32 v123, v8, v9
	v_lshlrev_b32_e32 v120, 16, v169
	v_and_b32_e32 v121, 0xffff0000, v169
	global_store_dword v116, v123, s[16:17]
	s_add_u32 s16, s16, 0x40000
	s_addc_u32 s17, s17, 0
	v_pk_mul_f32 v[120:121], v[104:105], v[120:121] op_sel:[1,0] op_sel_hi:[1,1]
	v_pk_fma_f32 v[8:9], v[8:9], v[40:41], v[120:121] op_sel:[0,1,0] op_sel_hi:[1,1,1]
	s_waitcnt vmcnt(63)
	v_cvt_pk_bf16_f32 v122, v8, v9
	v_lshlrev_b32_e32 v120, 16, v170
	v_and_b32_e32 v121, 0xffff0000, v170
	global_store_dword v116, v122, s[16:17]
	s_add_u32 s16, s16, 0x40000
	s_addc_u32 s17, s17, 0
	v_pk_mul_f32 v[120:121], v[106:107], v[120:121] op_sel_hi:[0,1]
	v_pk_fma_f32 v[8:9], v[8:9], v[42:43], v[120:121] op_sel_hi:[1,0,1]
	s_waitcnt vmcnt(63)
	v_cvt_pk_bf16_f32 v123, v8, v9
	v_lshlrev_b32_e32 v120, 16, v171
	v_and_b32_e32 v121, 0xffff0000, v171
	global_store_dword v116, v123, s[16:17]
	s_add_u32 s16, s16, 0x40000
	s_addc_u32 s17, s17, 0
	v_pk_mul_f32 v[120:121], v[106:107], v[120:121] op_sel:[1,0] op_sel_hi:[1,1]
	v_pk_fma_f32 v[8:9], v[8:9], v[42:43], v[120:121] op_sel:[0,1,0] op_sel_hi:[1,1,1]
	s_waitcnt vmcnt(63)
	v_cvt_pk_bf16_f32 v122, v8, v9
	v_lshlrev_b32_e32 v120, 16, v172
	v_and_b32_e32 v121, 0xffff0000, v172
	global_store_dword v116, v122, s[16:17]
	s_add_u32 s16, s16, 0x40000
	s_addc_u32 s17, s17, 0
	v_pk_mul_f32 v[120:121], v[108:109], v[120:121] op_sel_hi:[0,1]
	v_pk_fma_f32 v[8:9], v[8:9], v[44:45], v[120:121] op_sel_hi:[1,0,1]
	s_waitcnt vmcnt(63)
	v_cvt_pk_bf16_f32 v123, v8, v9
	v_lshlrev_b32_e32 v120, 16, v173
	v_and_b32_e32 v121, 0xffff0000, v173
	global_store_dword v116, v123, s[16:17]
	s_add_u32 s16, s16, 0x40000
	s_addc_u32 s17, s17, 0
	v_pk_mul_f32 v[120:121], v[108:109], v[120:121] op_sel:[1,0] op_sel_hi:[1,1]
	v_pk_fma_f32 v[8:9], v[8:9], v[44:45], v[120:121] op_sel:[0,1,0] op_sel_hi:[1,1,1]
	s_waitcnt vmcnt(63)
; DI unsigned pk2(float lo, float hi) { f32x2 v = {lo, hi}; bf16x2_t b = __builtin_convertvector(v, bf16x2_t); return __builtin_bit_cast(unsigned, b); }
; DI float bflo(unsigned u) { return __uint_as_float(u << 16); }
; DI float bfhi(unsigned u) { return __uint_as_float(u & 0xffff0000u); }
; DI void phase_m_comb(int wv, const ArgP a, LAS unsigned char* lds, int dry) {
;     ...
;             for (int c = 0; c < 256; c += 64) { unsigned d[64];
; #pragma unroll
;                 for (int k = 0; k < 64; ++k) d[k] = p[(size_t)(c + k) * 65536];
; #pragma unroll
;                 for (int k = 0; k < 64; ++k) { if (!dry) p[(size_t)(c + k) * 65536] = pk2(C0, C1); const float a_ = ga[(c + k) * 4 + h], b_ = gb[(c + k) * 4 + h]; C0 = a_ * C0 + b_ * bflo(d[k]); C1 = a_ * C1 + b_ * bfhi(d[k]); } }
	v_cvt_pk_bf16_f32 v122, v8, v9
	v_lshlrev_b32_e32 v120, 16, v174
	v_and_b32_e32 v121, 0xffff0000, v174
	global_store_dword v116, v122, s[16:17]
	s_add_u32 s16, s16, 0x40000
	s_addc_u32 s17, s17, 0
	v_pk_mul_f32 v[120:121], v[110:111], v[120:121] op_sel_hi:[0,1]
	v_pk_fma_f32 v[8:9], v[8:9], v[46:47], v[120:121] op_sel_hi:[1,0,1]
	s_waitcnt vmcnt(63)
	v_cvt_pk_bf16_f32 v123, v8, v9
	v_lshlrev_b32_e32 v120, 16, v175
	v_and_b32_e32 v121, 0xffff0000, v175
	global_store_dword v116, v123, s[16:17]
	s_add_u32 s16, s16, 0x40000
	s_addc_u32 s17, s17, 0
	v_pk_mul_f32 v[120:121], v[110:111], v[120:121] op_sel:[1,0] op_sel_hi:[1,1]
	v_pk_fma_f32 v[8:9], v[8:9], v[46:47], v[120:121] op_sel:[0,1,0] op_sel_hi:[1,1,1]
	s_waitcnt vmcnt(63)
	v_cvt_pk_bf16_f32 v122, v8, v9
	v_lshlrev_b32_e32 v120, 16, v176
	v_and_b32_e32 v121, 0xffff0000, v176
	global_store_dword v116, v122, s[16:17]
	s_add_u32 s16, s16, 0x40000
	s_addc_u32 s17, s17, 0
	v_pk_mul_f32 v[120:121], v[112:113], v[120:121] op_sel_hi:[0,1]
	v_pk_fma_f32 v[8:9], v[8:9], v[48:49], v[120:121] op_sel_hi:[1,0,1]
	s_waitcnt vmcnt(63)
	v_cvt_pk_bf16_f32 v123, v8, v9
	v_lshlrev_b32_e32 v120, 16, v177
	v_and_b32_e32 v121, 0xffff0000, v177
	global_store_dword v116, v123, s[16:17]
	s_add_u32 s16, s16, 0x40000
	s_addc_u32 s17, s17, 0
	v_pk_mul_f32 v[120:121], v[112:113], v[120:121] op_sel:[1,0] op_sel_hi:[1,1]
	v_pk_fma_f32 v[8:9], v[8:9], v[48:49], v[120:121] op_sel:[0,1,0] op_sel_hi:[1,1,1]
	s_waitcnt vmcnt(63)
	v_cvt_pk_bf16_f32 v122, v8, v9
	v_lshlrev_b32_e32 v120, 16, v178
	v_and_b32_e32 v121, 0xffff0000, v178
	global_store_dword v116, v122, s[16:17]
	s_add_u32 s16, s16, 0x40000
	s_addc_u32 s17, s17, 0
	v_pk_mul_f32 v[120:121], v[114:115], v[120:121] op_sel_hi:[0,1]
	v_pk_fma_f32 v[8:9], v[8:9], v[50:51], v[120:121] op_sel_hi:[1,0,1]
	s_waitcnt vmcnt(63)
	v_cvt_pk_bf16_f32 v123, v8, v9
	v_lshlrev_b32_e32 v120, 16, v179
	v_and_b32_e32 v121, 0xffff0000, v179
	global_store_dword v116, v123, s[16:17]
	s_add_u32 s16, s16, 0x40000
	s_addc_u32 s17, s17, 0
	v_pk_mul_f32 v[120:121], v[114:115], v[120:121] op_sel:[1,0] op_sel_hi:[1,1]
	v_pk_fma_f32 v[8:9], v[8:9], v[50:51], v[120:121] op_sel:[0,1,0] op_sel_hi:[1,1,1]
	s_waitcnt vmcnt(63)
	v_cvt_pk_bf16_f32 v122, v8, v9
	v_lshlrev_b32_e32 v120, 16, v180
	v_and_b32_e32 v121, 0xffff0000, v180
	global_store_dword v116, v122, s[16:17]
	s_add_u32 s16, s16, 0x40000
	s_addc_u32 s17, s17, 0
	v_pk_mul_f32 v[120:121], v[208:209], v[120:121] op_sel_hi:[0,1]
	v_pk_fma_f32 v[8:9], v[8:9], v[52:53], v[120:121] op_sel_hi:[1,0,1]
	s_waitcnt vmcnt(63)
	v_cvt_pk_bf16_f32 v123, v8, v9
	v_lshlrev_b32_e32 v120, 16, v181
	v_and_b32_e32 v121, 0xffff0000, v181
	global_store_dword v116, v123, s[16:17]
	s_add_u32 s16, s16, 0x40000
	s_addc_u32 s17, s17, 0
	v_pk_mul_f32 v[120:121], v[208:209], v[120:121] op_sel:[1,0] op_sel_hi:[1,1]
	v_pk_fma_f32 v[8:9], v[8:9], v[52:53], v[120:121] op_sel:[0,1,0] op_sel_hi:[1,1,1]
	s_waitcnt vmcnt(63)
	v_cvt_pk_bf16_f32 v122, v8, v9
	v_lshlrev_b32_e32 v120, 16, v182
	v_and_b32_e32 v121, 0xffff0000, v182
	global_store_dword v116, v122, s[16:17]
	s_add_u32 s16, s16, 0x40000
	s_addc_u32 s17, s17, 0
	v_pk_mul_f32 v[120:121], v[210:211], v[120:121] op_sel_hi:[0,1]
	v_pk_fma_f32 v[8:9], v[8:9], v[54:55], v[120:121] op_sel_hi:[1,0,1]
	s_waitcnt vmcnt(63)
	v_cvt_pk_bf16_f32 v123, v8, v9
	v_lshlrev_b32_e32 v120, 16, v183
	v_and_b32_e32 v121, 0xffff0000, v183
	global_store_dword v116, v123, s[16:17]
	s_add_u32 s16, s16, 0x40000
	s_addc_u32 s17, s17, 0
	v_pk_mul_f32 v[120:121], v[210:211], v[120:121] op_sel:[1,0] op_sel_hi:[1,1]
	v_pk_fma_f32 v[8:9], v[8:9], v[54:55], v[120:121] op_sel:[0,1,0] op_sel_hi:[1,1,1]
	s_waitcnt vmcnt(63)
	v_cvt_pk_bf16_f32 v122, v8, v9
	v_lshlrev_b32_e32 v120, 16, v184
	v_and_b32_e32 v121, 0xffff0000, v184
	global_store_dword v116, v122, s[16:17]
	s_add_u32 s16, s16, 0x40000
	s_addc_u32 s17, s17, 0
	v_pk_mul_f32 v[120:121], v[212:213], v[120:121] op_sel_hi:[0,1]
	v_pk_fma_f32 v[8:9], v[8:9], v[56:57], v[120:121] op_sel_hi:[1,0,1]
	s_waitcnt vmcnt(63)
	v_cvt_pk_bf16_f32 v123, v8, v9
	v_lshlrev_b32_e32 v120, 16, v185
	v_and_b32_e32 v121, 0xffff0000, v185
	global_store_dword v116, v123, s[16:17]
	s_add_u32 s16, s16, 0x40000
	s_addc_u32 s17, s17, 0
	v_pk_mul_f32 v[120:121], v[212:213], v[120:121] op_sel:[1,0] op_sel_hi:[1,1]
	v_pk_fma_f32 v[8:9], v[8:9], v[56:57], v[120:121] op_sel:[0,1,0] op_sel_hi:[1,1,1]
	s_waitcnt vmcnt(63)
	v_cvt_pk_bf16_f32 v122, v8, v9
	v_lshlrev_b32_e32 v120, 16, v186
	v_and_b32_e32 v121, 0xffff0000, v186
	global_store_dword v116, v122, s[16:17]
	s_add_u32 s16, s16, 0x40000
	s_addc_u32 s17, s17, 0
	v_pk_mul_f32 v[120:121], v[214:215], v[120:121] op_sel_hi:[0,1]
	v_pk_fma_f32 v[8:9], v[8:9], v[58:59], v[120:121] op_sel_hi:[1,0,1]
	s_waitcnt vmcnt(63)
	v_cvt_pk_bf16_f32 v123, v8, v9
	v_lshlrev_b32_e32 v120, 16, v187
	v_and_b32_e32 v121, 0xffff0000, v187
	global_store_dword v116, v123, s[16:17]
	s_add_u32 s16, s16, 0x40000
	s_addc_u32 s17, s17, 0
	v_pk_mul_f32 v[120:121], v[214:215], v[120:121] op_sel:[1,0] op_sel_hi:[1,1]
	v_pk_fma_f32 v[8:9], v[8:9], v[58:59], v[120:121] op_sel:[0,1,0] op_sel_hi:[1,1,1]
	s_waitcnt vmcnt(63)
	v_cvt_pk_bf16_f32 v122, v8, v9
	v_lshlrev_b32_e32 v120, 16, v188
	v_and_b32_e32 v121, 0xffff0000, v188
	global_store_dword v116, v122, s[16:17]
	s_add_u32 s16, s16, 0x40000
	s_addc_u32 s17, s17, 0
	v_pk_mul_f32 v[120:121], v[216:217], v[120:121] op_sel_hi:[0,1]
	v_pk_fma_f32 v[8:9], v[8:9], v[60:61], v[120:121] op_sel_hi:[1,0,1]
	s_waitcnt vmcnt(63)
; DI unsigned pk2(float lo, float hi) { f32x2 v = {lo, hi}; bf16x2_t b = __builtin_convertvector(v, bf16x2_t); return __builtin_bit_cast(unsigned, b); }
; DI float bflo(unsigned u) { return __uint_as_float(u << 16); }
; DI float bfhi(unsigned u) { return __uint_as_float(u & 0xffff0000u); }
; DI void phase_m_comb(int wv, const ArgP a, LAS unsigned char* lds, int dry) {
;     ...
;             for (int c = 0; c < 256; c += 64) { unsigned d[64];
; #pragma unroll
;                 for (int k = 0; k < 64; ++k) d[k] = p[(size_t)(c + k) * 65536];
; #pragma unroll
;                 for (int k = 0; k < 64; ++k) { if (!dry) p[(size_t)(c + k) * 65536] = pk2(C0, C1); const float a_ = ga[(c + k) * 4 + h], b_ = gb[(c + k) * 4 + h]; C0 = a_ * C0 + b_ * bflo(d[k]); C1 = a_ * C1 + b_ * bfhi(d[k]); } }
	v_cvt_pk_bf16_f32 v123, v8, v9
	v_lshlrev_b32_e32 v120, 16, v189
	v_and_b32_e32 v121, 0xffff0000, v189
	global_store_dword v116, v123, s[16:17]
	s_add_u32 s16, s16, 0x40000
	s_addc_u32 s17, s17, 0
	v_pk_mul_f32 v[120:121], v[216:217], v[120:121] op_sel:[1,0] op_sel_hi:[1,1]
	v_pk_fma_f32 v[8:9], v[8:9], v[60:61], v[120:121] op_sel:[0,1,0] op_sel_hi:[1,1,1]
	s_waitcnt vmcnt(63)
	v_cvt_pk_bf16_f32 v122, v8, v9
	v_lshlrev_b32_e32 v120, 16, v190
	v_and_b32_e32 v121, 0xffff0000, v190
	global_store_dword v116, v122, s[16:17]
	s_add_u32 s16, s16, 0x40000
	s_addc_u32 s17, s17, 0
	v_pk_mul_f32 v[120:121], v[218:219], v[120:121] op_sel_hi:[0,1]
	v_pk_fma_f32 v[8:9], v[8:9], v[62:63], v[120:121] op_sel_hi:[1,0,1]
	s_waitcnt vmcnt(63)
	v_cvt_pk_bf16_f32 v123, v8, v9
	v_lshlrev_b32_e32 v120, 16, v191
	v_and_b32_e32 v121, 0xffff0000, v191
	global_store_dword v116, v123, s[16:17]
	s_add_u32 s16, s16, 0x40000
	s_addc_u32 s17, s17, 0
	v_pk_mul_f32 v[120:121], v[218:219], v[120:121] op_sel:[1,0] op_sel_hi:[1,1]
	v_pk_fma_f32 v[8:9], v[8:9], v[62:63], v[120:121] op_sel:[0,1,0] op_sel_hi:[1,1,1]
	s_waitcnt vmcnt(63)
	v_cvt_pk_bf16_f32 v122, v8, v9
	v_lshlrev_b32_e32 v120, 16, v196
	v_and_b32_e32 v121, 0xffff0000, v196
	global_store_dword v116, v122, s[16:17]
	s_add_u32 s16, s16, 0x40000
	s_addc_u32 s17, s17, 0
	v_pk_mul_f32 v[120:121], v[220:221], v[120:121] op_sel_hi:[0,1]
	v_pk_fma_f32 v[8:9], v[8:9], v[64:65], v[120:121] op_sel_hi:[1,0,1]
	s_waitcnt vmcnt(63)
	v_cvt_pk_bf16_f32 v123, v8, v9
	v_lshlrev_b32_e32 v120, 16, v197
	v_and_b32_e32 v121, 0xffff0000, v197
	global_store_dword v116, v123, s[16:17]
	s_add_u32 s16, s16, 0x40000
	s_addc_u32 s17, s17, 0
	v_pk_mul_f32 v[120:121], v[220:221], v[120:121] op_sel:[1,0] op_sel_hi:[1,1]
	v_pk_fma_f32 v[8:9], v[8:9], v[64:65], v[120:121] op_sel:[0,1,0] op_sel_hi:[1,1,1]
	s_waitcnt vmcnt(63)
	v_cvt_pk_bf16_f32 v122, v8, v9
	v_lshlrev_b32_e32 v120, 16, v198
	v_and_b32_e32 v121, 0xffff0000, v198
	global_store_dword v116, v122, s[16:17]
	s_add_u32 s16, s16, 0x40000
	s_addc_u32 s17, s17, 0
	v_pk_mul_f32 v[120:121], v[222:223], v[120:121] op_sel_hi:[0,1]
	v_pk_fma_f32 v[8:9], v[8:9], v[66:67], v[120:121] op_sel_hi:[1,0,1]
	s_waitcnt vmcnt(63)
	v_cvt_pk_bf16_f32 v123, v8, v9
	v_lshlrev_b32_e32 v120, 16, v199
	v_and_b32_e32 v121, 0xffff0000, v199
	global_store_dword v116, v123, s[16:17]
	s_add_u32 s16, s16, 0x40000
	s_addc_u32 s17, s17, 0
	v_pk_mul_f32 v[120:121], v[222:223], v[120:121] op_sel:[1,0] op_sel_hi:[1,1]
	v_pk_fma_f32 v[8:9], v[8:9], v[66:67], v[120:121] op_sel:[0,1,0] op_sel_hi:[1,1,1]
	s_waitcnt vmcnt(63)
	v_cvt_pk_bf16_f32 v122, v8, v9
	v_lshlrev_b32_e32 v120, 16, v200
	v_and_b32_e32 v121, 0xffff0000, v200
	global_store_dword v116, v122, s[16:17]
	s_add_u32 s16, s16, 0x40000
	s_addc_u32 s17, s17, 0
	v_pk_mul_f32 v[120:121], v[224:225], v[120:121] op_sel_hi:[0,1]
	v_pk_fma_f32 v[8:9], v[8:9], v[68:69], v[120:121] op_sel_hi:[1,0,1]
	s_waitcnt vmcnt(63)
	v_cvt_pk_bf16_f32 v123, v8, v9
	v_lshlrev_b32_e32 v120, 16, v201
	v_and_b32_e32 v121, 0xffff0000, v201
	global_store_dword v116, v123, s[16:17]
	s_add_u32 s16, s16, 0x40000
	s_addc_u32 s17, s17, 0
	v_pk_mul_f32 v[120:121], v[224:225], v[120:121] op_sel:[1,0] op_sel_hi:[1,1]
	v_pk_fma_f32 v[8:9], v[8:9], v[68:69], v[120:121] op_sel:[0,1,0] op_sel_hi:[1,1,1]
	s_waitcnt vmcnt(63)
	v_cvt_pk_bf16_f32 v122, v8, v9
	v_lshlrev_b32_e32 v120, 16, v202
	v_and_b32_e32 v121, 0xffff0000, v202
	global_store_dword v116, v122, s[16:17]
	s_add_u32 s16, s16, 0x40000
	s_addc_u32 s17, s17, 0
	v_pk_mul_f32 v[120:121], v[226:227], v[120:121] op_sel_hi:[0,1]
	v_pk_fma_f32 v[8:9], v[8:9], v[70:71], v[120:121] op_sel_hi:[1,0,1]
	s_waitcnt vmcnt(63)
	v_cvt_pk_bf16_f32 v123, v8, v9
	v_lshlrev_b32_e32 v120, 16, v203
	v_and_b32_e32 v121, 0xffff0000, v203
	global_store_dword v116, v123, s[16:17]
	s_add_u32 s16, s16, 0x40000
	s_addc_u32 s17, s17, 0
	v_pk_mul_f32 v[120:121], v[226:227], v[120:121] op_sel:[1,0] op_sel_hi:[1,1]
	v_pk_fma_f32 v[8:9], v[8:9], v[70:71], v[120:121] op_sel:[0,1,0] op_sel_hi:[1,1,1]
	s_waitcnt vmcnt(63)
	v_cvt_pk_bf16_f32 v122, v8, v9
	v_lshlrev_b32_e32 v120, 16, v204
	v_and_b32_e32 v121, 0xffff0000, v204
	global_store_dword v116, v122, s[16:17]
	s_add_u32 s16, s16, 0x40000
	s_addc_u32 s17, s17, 0
	v_pk_mul_f32 v[120:121], v[228:229], v[120:121] op_sel_hi:[0,1]
	v_pk_fma_f32 v[8:9], v[8:9], v[72:73], v[120:121] op_sel_hi:[1,0,1]
	s_waitcnt vmcnt(63)
	v_cvt_pk_bf16_f32 v123, v8, v9
	v_lshlrev_b32_e32 v120, 16, v205
	v_and_b32_e32 v121, 0xffff0000, v205
	global_store_dword v116, v123, s[16:17]
	s_add_u32 s16, s16, 0x40000
	s_addc_u32 s17, s17, 0
	v_pk_mul_f32 v[120:121], v[228:229], v[120:121] op_sel:[1,0] op_sel_hi:[1,1]
	v_pk_fma_f32 v[8:9], v[8:9], v[72:73], v[120:121] op_sel:[0,1,0] op_sel_hi:[1,1,1]
	s_waitcnt vmcnt(63)
	v_cvt_pk_bf16_f32 v122, v8, v9
	v_lshlrev_b32_e32 v120, 16, v206
	v_and_b32_e32 v121, 0xffff0000, v206
	global_store_dword v116, v122, s[16:17]
	s_add_u32 s16, s16, 0x40000
	s_addc_u32 s17, s17, 0
	v_pk_mul_f32 v[120:121], v[230:231], v[120:121] op_sel_hi:[0,1]
	v_pk_fma_f32 v[8:9], v[8:9], v[74:75], v[120:121] op_sel_hi:[1,0,1]
	s_waitcnt vmcnt(63)
	v_cvt_pk_bf16_f32 v123, v8, v9
	v_lshlrev_b32_e32 v120, 16, v207
	v_and_b32_e32 v121, 0xffff0000, v207
	global_store_dword v116, v123, s[16:17]
	s_add_u32 s16, s16, 0x40000
	s_addc_u32 s17, s17, 0
	v_pk_mul_f32 v[120:121], v[230:231], v[120:121] op_sel:[1,0] op_sel_hi:[1,1]
	v_pk_fma_f32 v[8:9], v[8:9], v[74:75], v[120:121] op_sel:[0,1,0] op_sel_hi:[1,1,1]
	s_addk_i32 s18, 0x400
	s_addk_i32 s19, 0x400
	s_add_i32 s0, s0, 64
	s_cmpk_lt_u32 s0, 0x100
	s_cbranch_scc1 .Lmc_batch
	s_mov_b64 s[0:1], 0
